# attention: second-branch waves take row groups rotated by two so computing waves of partial tiles sit on different SIMDs
# baseline (speedup 1.0000x reference)
; __device__ __forceinline__ void dattn_unit(const bf16* __restrict__ Qb, const bf16* __restrict__ Kh, const bf16* __restrict__ Vh, int nq, int kv_lo, int kv_hi, int NT, ...
;     ...
;   const int tid = tid_, wid = __builtin_amdgcn_readfirstlane(tid >> 6), lane = tid & 63, r32 = lane & 31, hi = lane >> 5;
;   const int br = wid >> 2, rg = wid & 3;
;   const bool active = rg * 32 < nq;
;   const int kvalid = rg < 2 ? kv_lo : kv_hi;
;   float* wsf = (float*)(lds + 131072) + wid * 64; float* li_l = wsf; float* al_l = wsf + 32;
;   float m_reg = -1e30f, l_reg = 0; f32x16 o[8];
; #pragma unroll
;   for (int d = 0; d < 8; ++d) o[d] = f32x16{};
;   bf16x8 qr[8];
;   { const bf16* Qw = Qb + (long)(rg * 32 + r32) * 2048 + br * 128 + hi * 8;
; #pragma unroll
;     for (int d0 = 0; d0 < 8; ++d0) qr[d0] = *reinterpret_cast<const bf16x8*>(Qw + d0 * 16); }
.LBB0_903:
	v_mbcnt_lo_u32_b32 v4, -1, 0
	v_mbcnt_hi_u32_b32 v4, -1, v4
	s_mov_b64 s[12:13], -1
	v_add_u32_e32 v0, s38, v4
	v_and_b32_e32 v230, 31, v4
	v_readfirstlane_b32 s21, v0
	s_ashr_i32 s83, s21, 6
	s_lshr_b32 s2, s83, 1
	s_and_b32 s2, s2, 2
	s_add_i32 s2, s2, s83
	s_and_b32 s2, s2, 3
	s_lshl_b32 s80, s2, 5
	v_or_b32_e32 v0, s80, v230
	s_ashr_i32 s22, s21, 8
	v_lshlrev_b32_e32 v0, 12, v0
	v_lshl_add_u64 v[2:3], s[4:5], 0, v[0:1]
	s_lshl_b32 s4, s22, 7
	v_bfe_u32 v231, v4, 5, 1
	s_ashr_i32 s5, s4, 31
	v_lshl_add_u64 v[2:3], s[4:5], 1, v[2:3]
	v_lshlrev_b32_e32 v0, 4, v231
	v_lshl_add_u64 v[2:3], v[2:3], 0, v[0:1]
	global_load_dwordx4 v[162:165], v[2:3], off
	global_load_dwordx4 v[166:169], v[2:3], off offset:32
	global_load_dwordx4 v[170:173], v[2:3], off offset:64
	global_load_dwordx4 v[174:177], v[2:3], off offset:96
	global_load_dwordx4 v[178:181], v[2:3], off offset:128
	global_load_dwordx4 v[182:185], v[2:3], off offset:160
	global_load_dwordx4 v[186:189], v[2:3], off offset:192
	global_load_dwordx4 v[190:193], v[2:3], off offset:224
	s_ashr_i32 s14, s21, 7
	s_lshl_b32 s19, s83, 13
	s_cmp_lt_i32 s14, 2
	v_and_b32_e32 v233, 63, v4
	s_cselect_b64 s[4:5], -1, 0
	s_cmp_gt_i32 s14, 1
	s_cselect_b64 s[8:9], -1, 0
	v_lshlrev_b32_e32 v9, 3, v233
	v_lshrrev_b32_e32 v2, 1, v4
	s_and_b32 s18, s21, 0x7fffff80
	v_and_b32_e32 v7, 24, v9
	v_and_b32_e32 v6, 8, v2
	s_add_i32 s18, s18, 0x7fffff00
	v_and_b32_e32 v2, 32, v4
	v_bfe_u32 v5, v4, 2, 4
	s_and_b64 vcc, exec, s[8:9]
	v_or3_b32 v8, v2, v7, s18
	s_cbranch_vccz .LBB0_905
	s_lshr_b32 s12, s19, 8
	v_or_b32_e32 v2, s12, v5
	v_and_or_b32 v2, v2, 35, v6
	v_lshlrev_b32_e32 v3, 1, v8
	v_lshl_add_u32 v2, v2, 12, v3
	s_mov_b64 s[12:13], 0
